# E1: layer-1 attention main loop PV-phase ds_read2_b64 split into 2x ds_read_b64 (LDS rate)
# speedup vs baseline: 1.0286x; 1.0286x over previous
; #define LAS __attribute__((address_space(3)))
; __device__ __forceinline__ unsigned cvt_pk(float lo, float hi) { unsigned r; asm volatile("v_cvt_pk_bf16_f32 %0, %1, %2" : "=v"(r) : "v"(lo), "v"(hi)); return r; }
; __device__ __forceinline__ void attn_unit(LAS unsigned char* lds, int b, int h, int q0, int kbeg, int ntiles, const bf16_t* Q, const bf16_t* K, const bf16_t* Vt, bf16_t* cat) {
;     ...
;         const LAS unsigned char* kb = lds + (buf ^ 1) * AK_BYTES + r32 * (KP * 2) + hi * 16;
;         f32x16 pn0, pn1;
; #pragma unroll
;         for (int r = 0; r < 16; ++r) { pn0[r] = 0.f; pn1[r] = 0.f; }
;         float ps = 0.f; u32x4 pw[4];
;         bf16x8 ka = *(const LAS bf16x8*)(kb), kbb = *(const LAS bf16x8*)(kb + 32 * (KP * 2));
; #pragma unroll
;         for (int ds = 0; ds < 12; ++ds) {
;             bf16x8 na = ka, nb = kbb;
;             if (ds < 11) { na = *(const LAS bf16x8*)(kb + (ds + 1) * 32); nb = *(const LAS bf16x8*)(kb + 32 * (KP * 2) + (ds + 1) * 32); }
;             pn0 = __builtin_amdgcn_mfma_f32_32x32x16_bf16(ka, qf[ds], pn0, 0, 0, 0);
;             pn1 = __builtin_amdgcn_mfma_f32_32x32x16_bf16(kbb, qf[ds], pn1, 0, 0, 0);
;             if (ds < 8) {
;                 float e[4];
; #pragma unroll
;                 for (int j = 0; j < 4; ++j) { const float v = ds < 4 ? pc0[4 * ds + j] : pc1[4 * (ds - 4) + j]; e[j] = __builtin_amdgcn_exp2f(v - mrun); }
;                 ps += (e[0] + e[1]) + (e[2] + e[3]);
;                 const unsigned w0 = cvt_pk(e[0], e[1]), w1 = cvt_pk(e[2], e[3]);
;                 if ((ds & 1) == 0) { pw[ds >> 1].x = w0; pw[ds >> 1].y = w1; } else { pw[ds >> 1].z = w0; pw[ds >> 1].w = w1; }
;             }
;             ka = na; kbb = nb;
;             __builtin_amdgcn_sched_barrier(0);
;         }
.LBB0_1840:
	s_xor_b32 s6, s5, 1
	s_mul_i32 s7, s6, 0x6400
	v_add_u32_e32 v233, s7, v229
	ds_read_b128 v[98:101], v233
	v_sub_f32_e32 v82, v82, v231
	v_exp_f32_e32 v197, v82
	v_sub_f32_e32 v82, v84, v231
	v_exp_f32_e32 v201, v82
	v_sub_f32_e32 v82, v85, v231
	v_exp_f32_e32 v235, v82
	v_sub_f32_e32 v82, v86, v231
	v_exp_f32_e32 v196, v82
	v_sub_f32_e32 v82, v87, v231
	s_waitcnt lgkmcnt(0)
	v_mfma_f32_32x32x16_bf16 v[98:113], v[98:101], v[174:177], 0
	v_exp_f32_e32 v198, v82
	v_sub_f32_e32 v82, v88, v231
	v_sub_f32_e32 v83, v83, v231
	v_exp_f32_e32 v200, v82
	v_sub_f32_e32 v82, v89, v231
	v_exp_f32_e32 v199, v83
	v_exp_f32_e32 v234, v82
	ds_read_b128 v[188:191], v233 offset:32
	ds_read_b128 v[114:117], v233 offset:12800
	ds_read_b128 v[192:195], v233 offset:12832
	s_add_i32 s4, s4, 1
	v_pk_add_f32 v[82:83], v[196:197], v[198:199]
	v_pk_add_f32 v[84:85], v[200:201], v[234:235]
	s_waitcnt lgkmcnt(0)
	v_mfma_f32_32x32x16_bf16 v[114:129], v[114:117], v[174:177], 0
	v_add_f32_e64 v236, v82, v84
	v_add_f32_e64 v237, v83, v85
	v_cvt_pk_bf16_f32 v186, v197, v199
	v_cvt_pk_bf16_f32 v187, v201, v235
	v_add_f32_e32 v237, 0, v237
	v_mfma_f32_32x32x16_bf16 v[98:113], v[188:191], v[170:173], v[98:113]
	ds_read_b128 v[82:85], v233 offset:64
	ds_read_b128 v[86:89], v233 offset:12864
	v_add_f32_e32 v197, v236, v237
	v_cvt_pk_bf16_f32 v188, v196, v198
	v_cvt_pk_bf16_f32 v189, v200, v234
	v_mfma_f32_32x32x16_bf16 v[114:129], v[192:195], v[170:173], v[114:129]
	v_sub_f32_e32 v90, v90, v231
	s_waitcnt lgkmcnt(0)
	v_mfma_f32_32x32x16_bf16 v[98:113], v[82:85], v[166:169], v[98:113]
	v_exp_f32_e32 v190, v90
	v_sub_f32_e32 v90, v91, v231
	v_exp_f32_e32 v192, v90
	v_sub_f32_e32 v90, v92, v231
	v_sub_f32_e32 v82, v93, v231
	v_exp_f32_e32 v191, v90
	v_exp_f32_e32 v193, v82
	ds_read_b128 v[82:85], v233 offset:96
	ds_read_b128 v[90:93], v233 offset:12896
	v_mfma_f32_32x32x16_bf16 v[114:129], v[86:89], v[166:169], v[114:129]
	v_add_f32_e64 v194, v190, v192
	v_add_f32_e64 v195, v191, v193
	v_add_f32_e64 v198, v194, v194
	v_add_f32_e64 v199, v194, v195
	v_cvt_pk_bf16_f32 v190, v190, v192
	v_cvt_pk_bf16_f32 v191, v191, v193
	v_sub_f32_e32 v86, v94, v231
	s_waitcnt lgkmcnt(0)
	v_mfma_f32_32x32x16_bf16 v[98:113], v[82:85], v[162:165], v[98:113]
	v_exp_f32_e32 v94, v86
	v_sub_f32_e32 v86, v95, v231
	v_exp_f32_e32 v192, v86
	v_sub_f32_e32 v86, v96, v231
	v_sub_f32_e32 v82, v97, v231
	v_exp_f32_e32 v96, v86
	v_exp_f32_e32 v193, v82
	ds_read_b128 v[82:85], v233 offset:128
	ds_read_b128 v[86:89], v233 offset:12928
	v_add_f32_e32 v95, v94, v192
	v_cvt_pk_bf16_f32 v192, v94, v192
	v_add_f32_e32 v97, v96, v193
	v_mfma_f32_32x32x16_bf16 v[114:129], v[90:93], v[162:165], v[114:129]
	v_cvt_pk_bf16_f32 v193, v96, v193
	v_sub_f32_e32 v66, v66, v231
	v_exp_f32_e32 v94, v66
	v_sub_f32_e32 v66, v67, v231
	v_exp_f32_e32 v96, v66
	v_sub_f32_e32 v66, v68, v231
	v_exp_f32_e32 v198, v66
	s_waitcnt lgkmcnt(0)
	v_mfma_f32_32x32x16_bf16 v[98:113], v[82:85], v[158:161], v[98:113]
	v_sub_f32_e32 v66, v69, v231
	v_exp_f32_e32 v196, v66
	ds_read_b128 v[66:69], v233 offset:160
	ds_read_b128 v[82:85], v233 offset:12960
	v_pk_add_f32 v[90:91], v[94:95], v[96:97]
	v_cvt_pk_bf16_f32 v194, v94, v96
	v_pk_add_f32 v[92:93], v[198:199], v[196:197]
	v_cvt_pk_bf16_f32 v195, v198, v196
	v_mfma_f32_32x32x16_bf16 v[114:129], v[86:89], v[158:161], v[114:129]
	v_add_f32_e64 v90, v90, v92
	v_add_f32_e64 v91, v91, v93
	v_add_f32_e64 v86, v90, v90
	v_add_f32_e64 v87, v90, v91
	v_sub_f32_e32 v70, v70, v231
	v_exp_f32_e32 v88, v70
	v_sub_f32_e32 v70, v71, v231
	s_waitcnt lgkmcnt(0)
	v_mfma_f32_32x32x16_bf16 v[98:113], v[66:69], v[154:157], v[98:113]
	v_exp_f32_e32 v90, v70
	v_sub_f32_e32 v70, v72, v231
	v_sub_f32_e32 v66, v73, v231
	v_exp_f32_e32 v89, v70
	v_exp_f32_e32 v91, v66
	ds_read_b128 v[66:69], v233 offset:192
	ds_read_b128 v[70:73], v233 offset:12992
	v_cvt_pk_bf16_f32 v196, v88, v90
	v_mfma_f32_32x32x16_bf16 v[114:129], v[82:85], v[154:157], v[114:129]
	v_add_f32_e64 v92, v88, v90
	v_add_f32_e64 v93, v89, v91
	v_cvt_pk_bf16_f32 v197, v89, v91
	v_pk_add_f32 v[92:93], v[92:93], v[92:93] op_sel_hi:[0,1]
	v_sub_f32_e32 v74, v74, v231
	s_waitcnt lgkmcnt(0)
	v_mfma_f32_32x32x16_bf16 v[98:113], v[66:69], v[150:153], v[98:113]
	v_exp_f32_e32 v82, v74
	v_sub_f32_e32 v74, v75, v231
	v_exp_f32_e32 v84, v74
	v_sub_f32_e32 v74, v76, v231
	v_sub_f32_e32 v66, v77, v231
	v_exp_f32_e32 v86, v74
	v_exp_f32_e32 v88, v66
	ds_read_b128 v[66:69], v233 offset:224
	ds_read_b128 v[74:77], v233 offset:13024
	v_add_f32_e32 v83, v82, v84
	v_cvt_pk_bf16_f32 v198, v82, v84
	v_add_f32_e32 v85, v86, v88
	v_mfma_f32_32x32x16_bf16 v[114:129], v[70:73], v[150:153], v[114:129]
	v_cvt_pk_bf16_f32 v199, v86, v88
	v_sub_f32_e32 v70, v78, v231
	v_exp_f32_e32 v82, v70
	v_sub_f32_e32 v70, v79, v231
	s_waitcnt lgkmcnt(0)
	v_mfma_f32_32x32x16_bf16 v[98:113], v[66:69], v[146:149], v[98:113]
	v_exp_f32_e32 v84, v70
	v_sub_f32_e32 v70, v80, v231
	v_sub_f32_e32 v66, v81, v231
	v_exp_f32_e32 v92, v70
	v_exp_f32_e32 v86, v66
	ds_read_b128 v[66:69], v233 offset:256
	ds_read_b128 v[70:73], v233 offset:13056
	v_pk_add_f32 v[78:79], v[82:83], v[84:85]
	v_mfma_f32_32x32x16_bf16 v[114:129], v[74:77], v[146:149], v[114:129]
	v_add_f32_e64 v80, v92, v86
	v_add_f32_e64 v81, v93, v87
	v_cvt_pk_bf16_f32 v200, v82, v84
	v_cvt_pk_bf16_f32 v201, v92, v86
	v_add_f32_e64 v78, v78, v80
	v_add_f32_e64 v79, v79, v81
	v_add_f32_e32 v238, v78, v79
	s_waitcnt lgkmcnt(0)
	v_mfma_f32_32x32x16_bf16 v[98:113], v[66:69], v[142:145], v[98:113]
	ds_read_b128 v[66:69], v233 offset:288
	ds_read_b128 v[74:77], v233 offset:13088
	v_mfma_f32_32x32x16_bf16 v[114:129], v[70:73], v[142:145], v[114:129]
	s_waitcnt lgkmcnt(0)
; #define LAS __attribute__((address_space(3)))
; __device__ __forceinline__ unsigned cvt_pk(float lo, float hi) { unsigned r; asm volatile("v_cvt_pk_bf16_f32 %0, %1, %2" : "=v"(r) : "v"(lo), "v"(hi)); return r; }
; __device__ __forceinline__ void attn_unit(LAS unsigned char* lds, int b, int h, int q0, int kbeg, int ntiles, const bf16_t* Q, const bf16_t* K, const bf16_t* Vt, bf16_t* cat) {
;     ...
;         for (int ds = 0; ds < 12; ++ds) {
;             bf16x8 na = ka, nb = kbb;
;             if (ds < 11) { na = *(const LAS bf16x8*)(kb + (ds + 1) * 32); nb = *(const LAS bf16x8*)(kb + 32 * (KP * 2) + (ds + 1) * 32); }
;             pn0 = __builtin_amdgcn_mfma_f32_32x32x16_bf16(ka, qf[ds], pn0, 0, 0, 0);
;             pn1 = __builtin_amdgcn_mfma_f32_32x32x16_bf16(kbb, qf[ds], pn1, 0, 0, 0);
;             if (ds < 8) {
;                 float e[4];
; #pragma unroll
;                 for (int j = 0; j < 4; ++j) { const float v = ds < 4 ? pc0[4 * ds + j] : pc1[4 * (ds - 4) + j]; e[j] = __builtin_amdgcn_exp2f(v - mrun); }
;                 ps += (e[0] + e[1]) + (e[2] + e[3]);
;                 const unsigned w0 = cvt_pk(e[0], e[1]), w1 = cvt_pk(e[2], e[3]);
;                 if ((ds & 1) == 0) { pw[ds >> 1].x = w0; pw[ds >> 1].y = w1; } else { pw[ds >> 1].z = w0; pw[ds >> 1].w = w1; }
;             }
;             ka = na; kbb = nb;
;             __builtin_amdgcn_sched_barrier(0);
;         }
;         lrun += ps;
;         const LAS unsigned char* vb = lds + 2 * AK_BYTES + buf * AV_BYTES + r32 * AV_PITCH + hi * 8;
; #pragma unroll
;         for (int d = 0; d < 4; ++d)
; #pragma unroll
;             for (int ks = 0; ks < 4; ++ks) {
;                 const s16x4 lo = *(const LAS s16x4*)(vb + d * 32 * AV_PITCH + ks * 32), hh = *(const LAS s16x4*)(vb + d * 32 * AV_PITCH + ks * 32 + 16);
;                 const bf16x8 vf = (bf16x8){lo[0], lo[1], lo[2], lo[3], hh[0], hh[1], hh[2], hh[3]};
;                 o[d] = __builtin_amdgcn_mfma_f32_32x32x16_bf16(vf, __builtin_bit_cast(bf16x8, pw[ks]), o[d], 0, 0, 0);
;             }
;         { float mx = fmaxf(pn0[0], pn1[0]);
; #pragma unroll
;           for (int r = 1; r < 16; ++r) mx = fmaxf(mx, fmaxf(pn0[r], pn1[r]));
;           mxc = fmaxf(mx, __shfl_xor(mx, 32)); }
;         if (kt + 1 < ntiles) ASTOREV(buf ^ 1);
;         asm volatile("s_waitcnt vmcnt(0)" ::: "memory");
;         __syncthreads();
	v_mfma_f32_32x32x16_bf16 v[98:113], v[66:69], v[138:141], v[98:113]
	ds_read_b128 v[66:69], v233 offset:320
	ds_read_b128 v[70:73], v233 offset:13120
	v_mfma_f32_32x32x16_bf16 v[114:129], v[74:77], v[138:141], v[114:129]
	s_waitcnt lgkmcnt(0)
	v_mfma_f32_32x32x16_bf16 v[98:113], v[66:69], v[134:137], v[98:113]
	ds_read_b128 v[66:69], v233 offset:352
	ds_read_b128 v[234:237], v233 offset:13152
	v_mfma_f32_32x32x16_bf16 v[114:129], v[70:73], v[134:137], v[114:129]
	s_nop 8
	v_mov_b64_e32 v[82:83], v[98:99]
	v_mov_b64_e32 v[84:85], v[100:101]
	v_mov_b64_e32 v[86:87], v[102:103]
	v_mov_b64_e32 v[88:89], v[104:105]
	v_mov_b64_e32 v[90:91], v[106:107]
	v_mov_b64_e32 v[92:93], v[108:109]
	v_mov_b64_e32 v[94:95], v[110:111]
	v_mov_b64_e32 v[96:97], v[112:113]
	s_waitcnt lgkmcnt(0)
	s_nop 0
	v_mfma_f32_32x32x16_bf16 v[82:97], v[66:69], v[130:133], v[82:97]
	v_mov_b64_e32 v[66:67], v[114:115]
	v_mov_b64_e32 v[68:69], v[116:117]
	v_mov_b64_e32 v[70:71], v[118:119]
	v_mov_b64_e32 v[72:73], v[120:121]
	v_mov_b64_e32 v[74:75], v[122:123]
	v_mov_b64_e32 v[76:77], v[124:125]
	v_mov_b64_e32 v[78:79], v[126:127]
	v_mov_b64_e32 v[80:81], v[128:129]
	s_nop 1
	v_mfma_f32_32x32x16_bf16 v[66:81], v[234:237], v[130:133], v[66:81]
	s_mulk_i32 s5, 0x4400
	v_add_u32_e32 v233, s5, v230
	v_add_u32_e32 v102, 0xc800, v233
	ds_read_b64 v[98:99], v102
	ds_read_b64 v[100:101], v102 offset:16
	v_add_u32_e32 v110, 0xd800, v233
	v_add_u32_e32 v126, 0xe800, v233
	s_nop 5
	v_max_f32_e32 v239, v67, v67
	v_max_f32_e32 v240, v83, v83
	v_max_f32_e32 v239, v240, v239
	v_max3_f32 v239, v82, v66, v239
	v_add_u32_e32 v233, 0xf800, v233
	s_mulk_i32 s6, 0x4400
	s_waitcnt lgkmcnt(0)
	v_mfma_f32_32x32x16_bf16 v[50:65], v[98:101], v[186:189], v[50:65]
	ds_read_b64 v[98:99], v102 offset:32
	ds_read_b64 v[100:101], v102 offset:48
	v_add_f32_e32 v202, v202, v238
	v_lshl_add_u64 v[214:215], v[214:215], 0, s[38:39]
	v_lshl_add_u64 v[216:217], v[216:217], 0, s[38:39]
	v_lshl_add_u64 v[218:219], v[218:219], 0, s[38:39]
	v_lshl_add_u64 v[220:221], v[220:221], 0, s[38:39]
	v_lshl_add_u64 v[222:223], v[222:223], 0, s[40:41]
	s_cmp_lg_u32 s4, 34
	s_waitcnt lgkmcnt(0)
	v_mfma_f32_32x32x16_bf16 v[50:65], v[98:101], v[190:193], v[50:65]
	ds_read_b64 v[98:99], v102 offset:64
	ds_read_b64 v[100:101], v102 offset:80
	s_waitcnt lgkmcnt(0)
	v_mfma_f32_32x32x16_bf16 v[50:65], v[98:101], v[194:197], v[50:65]
	ds_read_b64 v[98:99], v102 offset:96
	ds_read_b64 v[100:101], v102 offset:112
	ds_read_b64 v[102:103], v110 offset:256
	ds_read_b64 v[104:105], v110 offset:272
	s_waitcnt lgkmcnt(0)
	v_mfma_f32_32x32x16_bf16 v[34:49], v[102:105], v[186:189], v[34:49]
	v_mfma_f32_32x32x16_bf16 v[50:65], v[98:101], v[198:201], v[50:65]
	ds_read_b64 v[98:99], v110 offset:288
	ds_read_b64 v[100:101], v110 offset:304
	ds_read_b64 v[106:107], v110 offset:320
	ds_read_b64 v[108:109], v110 offset:336
	ds_read_b64 v[112:113], v110 offset:368
	ds_read_b64 v[110:111], v110 offset:352
	ds_read_b64 v[114:115], v126 offset:512
	ds_read_b64 v[116:117], v126 offset:528
	ds_read_b64 v[118:119], v126 offset:544
	ds_read_b64 v[120:121], v126 offset:560
	ds_read_b64 v[122:123], v126 offset:576
	ds_read_b64 v[124:125], v126 offset:592
	ds_read_b64 v[128:129], v126 offset:624
	ds_read_b64 v[126:127], v126 offset:608
	ds_read_b64 v[102:103], v233 offset:768
	ds_read_b64 v[104:105], v233 offset:784
	ds_read_b64 v[234:235], v233 offset:800
	ds_read_b64 v[236:237], v233 offset:816
	s_waitcnt lgkmcnt(0)
	v_mfma_f32_32x32x16_bf16 v[34:49], v[98:101], v[190:193], v[34:49]
	v_max_f32_e32 v98, v68, v68
	v_max_f32_e32 v99, v84, v84
	v_max_f32_e32 v98, v99, v98
	v_max_f32_e32 v99, v69, v69
	v_max_f32_e32 v100, v85, v85
	v_max_f32_e32 v99, v100, v99
	v_max3_f32 v98, v239, v98, v99
	v_max_f32_e32 v99, v70, v70
	v_max_f32_e32 v100, v86, v86
	v_max_f32_e32 v99, v100, v99
	v_max_f32_e32 v100, v71, v71
	v_max_f32_e32 v101, v87, v87
	v_max_f32_e32 v100, v101, v100
	v_max3_f32 v98, v98, v99, v100
	v_max_f32_e32 v99, v72, v72
	v_max_f32_e32 v100, v88, v88
	v_max_f32_e32 v99, v100, v99
	v_max_f32_e32 v100, v73, v73
	v_max_f32_e32 v101, v89, v89
	v_max_f32_e32 v100, v101, v100
	v_max3_f32 v98, v98, v99, v100
	v_mfma_f32_32x32x16_bf16 v[18:33], v[114:117], v[186:189], v[18:33]
	v_max_f32_e32 v99, v74, v74
	v_max_f32_e32 v100, v90, v90
	v_max_f32_e32 v99, v100, v99
	v_max_f32_e32 v100, v75, v75
	v_max_f32_e32 v101, v91, v91
	v_max_f32_e32 v100, v101, v100
	v_max3_f32 v98, v98, v99, v100
	v_mfma_f32_32x32x16_bf16 v[2:17], v[102:105], v[186:189], v[2:17]
	v_max_f32_e32 v99, v76, v76
	v_max_f32_e32 v100, v92, v92
	v_max_f32_e32 v99, v100, v99
	v_max_f32_e32 v100, v77, v77
	v_max_f32_e32 v101, v93, v93
	v_max_f32_e32 v100, v101, v100
	v_max3_f32 v98, v98, v99, v100
	v_max_f32_e32 v99, v78, v78
	v_max_f32_e32 v100, v94, v94
	v_max_f32_e32 v99, v100, v99
	v_max_f32_e32 v100, v79, v79
	v_max_f32_e32 v101, v95, v95
	v_mfma_f32_32x32x16_bf16 v[18:33], v[118:121], v[190:193], v[18:33]
	v_max_f32_e32 v100, v101, v100
	v_max3_f32 v98, v98, v99, v100
	v_max_f32_e32 v99, v80, v80
	v_max_f32_e32 v100, v96, v96
	v_max_f32_e32 v99, v100, v99
	v_max_f32_e32 v100, v81, v81
	v_max_f32_e32 v101, v97, v97
	v_mfma_f32_32x32x16_bf16 v[2:17], v[234:237], v[190:193], v[2:17]
	v_max_f32_e32 v100, v101, v100
	v_max3_f32 v98, v98, v99, v100
	ds_bpermute_b32 v99, v209, v98
	s_waitcnt lgkmcnt(0)
	v_max_f32_e32 v99, v99, v99
	v_mfma_f32_32x32x16_bf16 v[34:49], v[106:109], v[194:197], v[34:49]
	ds_read_b64 v[100:101], v233 offset:832
	ds_read_b64 v[102:103], v233 offset:848
	ds_read_b64 v[104:105], v233 offset:864
	ds_read_b64 v[106:107], v233 offset:880
	v_max_f32_e32 v98, v98, v99
	v_add_u32_e32 v99, s6, v232
	v_add_u32_e32 v108, 0xc800, v99
	v_add_u32_e32 v99, 0xea00, v99
	s_waitcnt vmcnt(0)
	ds_write2_b64 v108, v[178:179], v[180:181] offset1:1
	ds_write2_b64 v99, v[182:183], v[184:185] offset1:1
	s_waitcnt vmcnt(0)
	v_mfma_f32_32x32x16_bf16 v[18:33], v[122:125], v[194:197], v[18:33]
	s_waitcnt lgkmcnt(0)
	s_barrier
	v_mfma_f32_32x32x16_bf16 v[2:17], v[100:103], v[194:197], v[2:17]
	v_mfma_f32_32x32x16_bf16 v[34:49], v[110:113], v[198:201], v[34:49]
	v_mfma_f32_32x32x16_bf16 v[18:33], v[126:129], v[198:201], v[18:33]
	v_mfma_f32_32x32x16_bf16 v[2:17], v[104:107], v[198:201], v[2:17]
	s_cbranch_scc0 .LBB0_1845
